# work queue: workgroups that cannot receive a GDN chain ticket (index within XCD >= chains per XCD) start on the global counter instead of first drawing a useless per-XCD ticket
# speedup vs baseline: 1.0111x; 1.0003x over previous
; #define LAUNDER_TID() int tid = tid0; asm volatile("" : "+v"(tid)); const int lane = tid & 63, wave = __builtin_amdgcn_readfirstlane(tid >> 6), gw = bx * NWAVES + wave; (void)lane; (void)gw
; #define TBR(i) __builtin_amdgcn_readfirstlane((int)TB[i])
; #define UNIFORM_F(x) __builtin_bit_cast(float, __builtin_amdgcn_readfirstlane(__builtin_bit_cast(int, (float)(x))))
; __global__ void __launch_bounds__(NTHREADS, 2) fwd_kernel(Args args) {
;     ...
;             const bool fixd = (bd * LOG2E < 60.f) && (bd == bd), fixs = (bs * LOG2E < 60.f) && (bs == bs);
;     ...
;             AttnParams PD{dqg, nullptr, diff_lambda + l * 256, diff_norm_gain + l * 128, UNIFORM_F(bd)};
;             AttnParams PS{sqg, swa_sink + l * 8, nullptr, nullptr, UNIFORM_F(bs)};
;             DIFF_TABLE(bd, fixd);
;             const int ndiff = TBR(T_NDF);
;             const int item_lo = (rep == 1 && (DUP_PHASE == 8 || DUP_PHASE == 11)) ? nchain : ((rep == 1 && DUP_PHASE == 9) ? nchain + ndiff : 0);
;             const int total = (rep == 1 && DUP_PHASE == 5) ? nchain : ((rep == 1 && (DUP_PHASE == 8 || DUP_PHASE == 11)) ? nchain + ndiff : nchain + ndiff + nblk);
; #pragma unroll 1
;             for (;;) {
;                 LAUNDER_TID();
;                 if (tid == 0) MISC[0] = __hip_atomic_fetch_add(ctl + CW_QUEUE + it * 64 + rep * 32, 1u, __ATOMIC_RELAXED, __HIP_MEMORY_SCOPE_AGENT);
;                 __syncthreads();
;                 const int item = __builtin_amdgcn_readfirstlane((int)MISC[0]) + item_lo;
;                 __syncthreads();
;                 if (item >= total) break;
.LBB0_822:
	s_or_b64 exec, exec, s[18:19]
	s_xor_b64 s[6:7], s[6:7], -1
	v_writelane_b32 v255, s6, 10
	s_add_i32 s22, s22, 3
	s_lshl_b32 s18, s31, 6
	v_writelane_b32 v255, s7, 11
	v_readlane_b32 s6, v254, 26
	s_mov_b32 s19, s61
	s_lshl_b32 s16, s85, s22
	s_lshl_b32 s60, s6, 8
	s_lshl_b32 s6, s6, 3
	s_lshl_b64 s[18:19], s[18:19], 2
	v_readlane_b32 s3, v252, 32
	s_add_u32 s18, s3, s18
	v_readlane_b32 s3, v252, 33
	s_addc_u32 s19, s3, s19
	v_readlane_b32 s7, v254, 27
	v_writelane_b32 v254, s18, 32
	s_lshr_b32 s17, s35, 5
	v_cmp_u_f32_e32 vcc, v2, v2
	v_writelane_b32 v254, s19, 33
	s_mov_b32 s7, s61
	v_readlane_b32 s22, v254, 16
	v_readlane_b32 s23, v254, 17
	s_and_b64 s[18:19], s[22:23], exec
	s_cselect_b32 s3, 8, 6
	s_cselect_b32 s29, 14, 12
	v_writelane_b32 v255, s3, 20
	s_add_i32 s3, s72, -1
	v_writelane_b32 v255, s3, 22
	s_add_i32 s3, s72, -3
	s_xor_b64 s[4:5], s[4:5], -1
	v_writelane_b32 v255, s3, 26
	s_or_b64 s[4:5], vcc, s[4:5]
	v_writelane_b32 v255, s4, 30
	s_add_i32 s19, s72, -2
	s_waitcnt lgkmcnt(0)
	v_writelane_b32 v255, s5, 31
	s_lshl_b64 s[4:5], s[60:61], 2
	s_add_u32 s4, s10, s4
	s_addc_u32 s5, s11, s5
	v_writelane_b32 v254, s4, 40
	s_add_u32 s38, s12, s8
	s_addc_u32 s39, s13, s9
	v_writelane_b32 v254, s5, 41
	s_lshl_b64 s[4:5], s[6:7], 2
	s_add_u32 s4, s14, s4
	s_addc_u32 s5, s15, s5
	v_writelane_b32 v254, s4, 42
	s_barrier
	s_nop 0
	v_writelane_b32 v254, s5, 43
	s_and_b64 s[4:5], s[22:23], exec
	v_readlane_b32 s3, v254, 1
	s_cselect_b32 s84, 32, 0x80
	v_writelane_b32 v255, s17, 14
	v_mov_b32_e32 v2, s3
	ds_read_b32 v2, v2
	s_waitcnt lgkmcnt(0)
	v_readfirstlane_b32 s4, v2
	v_cvt_f32_u32_e32 v2, s17
	s_add_i32 s3, s4, s84
	s_sub_i32 s4, 0, s17
	v_writelane_b32 v254, s3, 30
	v_rcp_iflag_f32_e32 v2, v2
	s_add_i32 s23, s3, s16
	v_mul_f32_e32 v2, 0x4f7ffffe, v2
	v_cvt_u32_f32_e32 v2, v2
	s_nop 0
	v_readfirstlane_b32 s5, v2
	s_mul_i32 s4, s4, s5
	s_mul_hi_u32 s4, s5, s4
	s_add_i32 s3, s5, s4
	v_writelane_b32 v255, s3, 38
	s_ashr_i32 s3, s85, 31
	v_writelane_b32 v255, s3, 40
	s_abs_i32 s3, s85
	v_cvt_f32_u32_e32 v2, s3
	s_sub_i32 s4, 0, s3
	v_writelane_b32 v255, s3, 42
	v_rcp_iflag_f32_e32 v2, v2
	s_nop 0
	v_mul_f32_e32 v2, 0x4f7ffffe, v2
	v_cvt_u32_f32_e32 v2, v2
	s_nop 0
	v_readfirstlane_b32 s5, v2
	s_mul_i32 s4, s4, s5
	s_mul_hi_u32 s4, s5, s4
	s_add_i32 s3, s5, s4
	v_writelane_b32 v255, s3, 46
	v_readlane_b32 s3, v254, 34
	s_sub_i32 s4, 0, s3
	s_nop 0
	v_cvt_f32_u32_e32 v2, s3
	v_rcp_iflag_f32_e32 v2, v2
	s_nop 0
	v_mul_f32_e32 v2, 0x4f7ffffe, v2
	v_cvt_u32_f32_e32 v2, v2
	s_nop 0
	v_readfirstlane_b32 s5, v2
	v_cvt_f32_u32_e32 v2, s85
	s_mul_i32 s4, s4, s5
	s_mul_hi_u32 s4, s5, s4
	s_add_i32 s3, s5, s4
	v_rcp_iflag_f32_e32 v2, v2
	s_sub_i32 s4, 0, s85
	v_writelane_b32 v255, s3, 50
	v_mul_f32_e32 v2, 0x4f7ffffe, v2
	v_cvt_u32_f32_e32 v2, v2
	s_nop 0
	v_readfirstlane_b32 s5, v2
	s_mul_i32 s4, s4, s5
	s_mul_hi_u32 s4, s5, s4
	s_add_i32 s3, s5, s4
	v_writelane_b32 v255, s3, 52
	s_add_i32 s3, s35, -1
	v_writelane_b32 v255, s85, 0
	v_writelane_b32 v254, s3, 36
	s_add_i32 s3, s72, -5
	v_writelane_b32 v255, s29, 18
	v_writelane_b32 v254, s3, 38
	v_writelane_b32 v255, s84, 34
	s_lshr_b32 s32, s2, 3
	s_lshr_b32 s100, s84, 3
	s_cmp_ge_u32 s32, s100
	s_cselect_b32 s32, 1, 0
	s_branch .LBB0_825
